# norm B loop: x(next) unpack ladder + Y(next) rotation moved behind one counted vmcnt(16) at the end of the row, block-head vmcnt(0) removed (true 1-row prefetch)
# speedup vs baseline: 1.0109x; 1.0109x over previous
; #define GAS __attribute__((address_space(1)))
; DI void phase_norm(const Frame& F0, int nrows, const void* xlat, const void* xctx, int xin_bf16, const bf16* Y, const float* gainY, const float* gate  ,
;                    void* Xout_lat, void* Xout_ctx, int xout_bf16, bf16* Hout, const float* gainH, const float* shift, const float* scale) {
;     ...
;     const int gw = F.vcu * NWAVES + F.wave, NGW = F.G * NWAVES;
;     const int co = F.lane * 4;
;     const int nfull = nrows / NGW, xr = F.wave * F.G + F.vcu, nit = nfull + (xr < nrows - nfull * NGW ? 1 : 0);
;     const bool onebatch = nfull == 4 && (NGW / 2) * 4 == SEQ; const int hw = NGW / 2;
;     ...
;     f32x4 v[8]; v2u yb[8];
;     if (nit > 0) { const int R0 = NORM_ROW(0); norm_load_x(v, xlat, xctx, xin_bf16, R0, co);
;         if (Y) {
; #pragma unroll
;             for (int j = 0; j < 8; ++j) yb[j] = *(const GAS v2u*)(Y + (size_t)R0 * DM + j * 256 + co); } }
;     f32x4 gt[8], sh[8], sc[8]; int mbp = -1;
;     for (int it = 0; it < nit; ++it) {
;         const int R = NORM_ROW(it); const int mb = row_mb(R), Rn = NORM_ROW(it + 1);
;         f32x4 vn[8]; v2u ybn[8];
;         if (it + 1 < nit) { norm_load_x(vn, xlat, xctx, xin_bf16, Rn, co);
;             if (Y) {
; #pragma unroll
;                 for (int j = 0; j < 8; ++j) ybn[j] = *(const GAS v2u*)(Y + (size_t)Rn * DM + j * 256 + co); } }
;         if (mb != mbp) { mbp = mb;
;             if (Y) {
; #pragma unroll
;                 for (int j = 0; j < 8; ++j) gt[j] = *(const GAS f32x4*)(gate + (size_t)mb * NADA + j * 256 + co); }
;             if (Hout) {
; #pragma unroll
;                 for (int j = 0; j < 8; ++j) { sh[j] = *(const GAS f32x4*)(shift + (size_t)mb * NADA + j * 256 + co); sc[j] = *(const GAS f32x4*)(scale + (size_t)mb * NADA + j * 256 + co); } } }
;         if (Y) {
;             f32x4 y[8]; float ss = 0.f;
; #pragma unroll
;             for (int j = 0; j < 8; ++j) { y[j] = (f32x4){bflo(yb[j].x), bfhi(yb[j].x), bflo(yb[j].y), bfhi(yb[j].y)};
;                 ss += (y[j].x * y[j].x + y[j].y * y[j].y) + (y[j].z * y[j].z + y[j].w * y[j].w); }
.LBB0_1076:
	s_add_u32 s8, s8, 0x2de84000
	s_addc_u32 s9, s9, 0
	s_add_u32 s18, s4, 0x15de4000
	s_addc_u32 s19, s5, 0
	s_add_u32 s20, s6, 0x17de4000
	s_addc_u32 s21, s7, 0
	s_lshl_b64 s[4:5], s[34:35], 12
	s_add_u32 s4, s8, s4
	s_addc_u32 s5, s9, s5
	v_lshlrev_b64 v[4:5], 1, v[164:165]
	v_lshl_add_u64 v[6:7], s[4:5], 0, v[4:5]
	global_load_dwordx2 v[192:193], v[6:7], off offset:3584 nt
	global_load_dwordx2 v[194:195], v[6:7], off offset:3072 nt
	global_load_dwordx2 v[196:197], v[6:7], off offset:2560 nt
	global_load_dwordx2 v[198:199], v[6:7], off offset:2048 nt
	global_load_dwordx2 v[200:201], v[6:7], off offset:1536 nt
	global_load_dwordx2 v[202:203], v[6:7], off offset:1024 nt
	global_load_dwordx2 v[204:205], v[6:7], off offset:512 nt
	global_load_dwordx2 v[206:207], v[6:7], off nt
	v_lshl_add_u64 v[166:167], s[8:9], 0, v[4:5]
	v_lshl_add_u64 v[4:5], s[0:1], 0, v[4:5]
	s_mov_b64 s[0:1], 0x1a1e4000
	v_and_b32_e32 v2, 64, v224
	v_lshl_add_u64 v[174:175], v[4:5], 0, s[0:1]
	v_add_u32_e32 v4, 64, v2
	v_xor_b32_e32 v2, 1, v224
	v_cmp_lt_i32_e32 vcc, v2, v4
	v_xor_b32_e32 v5, 2, v224
	s_ashr_i32 s0, s17, 31
	v_readlane_b32 s1, v254, 48
	v_cndmask_b32_e32 v2, v224, v2, vcc
	v_cmp_lt_i32_e32 vcc, v5, v4
	s_xor_b32 s0, s0, s1
	s_abs_i32 s1, s17
	v_readlane_b32 s5, v254, 28
	v_cndmask_b32_e32 v5, v224, v5, vcc
	s_mul_hi_u32 s5, s1, s5
	v_readlane_b32 s8, v254, 27
	v_lshlrev_b32_e32 v208, 2, v5
	v_xor_b32_e32 v5, 4, v224
	s_mul_i32 s6, s5, s8
	v_cmp_lt_i32_e32 vcc, v5, v4
	s_sub_i32 s1, s1, s6
	s_add_i32 s24, s24, s13
	s_and_b32 s4, s17, 0x3ff
	v_cndmask_b32_e32 v5, v224, v5, vcc
	s_add_i32 s6, s5, 1
	s_sub_i32 s7, s1, s8
	v_lshlrev_b32_e32 v209, 2, v5
	v_xor_b32_e32 v5, 8, v224
	s_cmp_ge_u32 s1, s8
	v_cmp_lt_i32_e32 vcc, v5, v4
	s_cselect_b32 s5, s6, s5
	s_cselect_b32 s1, s7, s1
	v_cndmask_b32_e32 v5, v224, v5, vcc
	s_add_i32 s6, s5, 1
	v_lshlrev_b32_e32 v210, 2, v5
	v_xor_b32_e32 v5, 16, v224
	s_cmp_ge_u32 s1, s8
	v_cmp_lt_i32_e32 vcc, v5, v4
	s_cselect_b32 s1, s6, s5
	s_xor_b32 s1, s1, s0
	v_cndmask_b32_e32 v5, v224, v5, vcc
	v_lshlrev_b32_e32 v211, 2, v5
	v_xor_b32_e32 v5, 32, v224
	s_lshl_b32 s1, s1, 12
	v_cmp_lt_i32_e32 vcc, v5, v4
	s_or_b32 s1, s1, s4
	s_lshl_b32 s0, s0, 12
	v_lshlrev_b64 v[6:7], 2, v[164:165]
	v_cndmask_b32_e32 v4, v224, v5, vcc
	s_sub_i32 s28, s1, s0
	s_bitset1_b32 s1, 10
	v_mov_b32_e32 v84, 0
	v_lshl_add_u64 v[168:169], s[38:39], 0, v[6:7]
	v_lshl_add_u64 v[170:171], s[40:41], 0, v[6:7]
	v_lshl_add_u64 v[172:173], s[42:43], 0, v[6:7]
	s_mov_b32 s25, 0
	s_mov_b32 s10, -1
	v_lshlrev_b32_e32 v2, 2, v2
	v_lshlrev_b32_e32 v212, 2, v4
	s_sub_i32 s29, s1, s0
	v_mov_b32_e32 v85, v84
	v_mov_b32_e32 v86, v84
	v_mov_b32_e32 v87, v84
	v_mov_b32_e32 v104, v84
	v_mov_b32_e32 v105, v84
	v_mov_b32_e32 v106, v84
	v_mov_b32_e32 v107, v84
	v_mov_b32_e32 v108, v84
	v_mov_b32_e32 v109, v84
	v_mov_b32_e32 v110, v84
	v_mov_b32_e32 v111, v84
	v_mov_b32_e32 v112, v84
	v_mov_b32_e32 v113, v84
	v_mov_b32_e32 v114, v84
	v_mov_b32_e32 v115, v84
	v_mov_b32_e32 v144, v84
	v_mov_b32_e32 v145, v84
	v_mov_b32_e32 v146, v84
	v_mov_b32_e32 v147, v84
	v_mov_b32_e32 v152, v84
	v_mov_b32_e32 v153, v84
	v_mov_b32_e32 v154, v84
	v_mov_b32_e32 v155, v84
	v_mov_b32_e32 v156, v84
	v_mov_b32_e32 v157, v84
	v_mov_b32_e32 v158, v84
	v_mov_b32_e32 v159, v84
	v_mov_b32_e32 v160, v84
	v_mov_b32_e32 v161, v84
	s_waitcnt lgkmcnt(0)
	v_mov_b32_e32 v162, v84
	v_mov_b32_e32 v163, v84
	s_waitcnt vmcnt(0)
	s_branch .LBB0_1078
.LBB0_1077:
	v_lshlrev_b32_e32 v226, 16, v206
	v_and_b32_e32 v227, 0xffff0000, v206
	v_lshlrev_b32_e32 v206, 16, v207
	v_and_b32_e32 v207, 0xffff0000, v207
	v_mul_f32_e32 v228, v207, v207
	v_lshlrev_b32_e32 v231, 16, v205
	v_lshlrev_b32_e32 v230, 16, v204
	v_and_b32_e32 v205, 0xffff0000, v205
	v_and_b32_e32 v204, 0xffff0000, v204
	v_lshlrev_b32_e32 v237, 16, v200
	v_mul_f32_e32 v236, v227, v227
	v_pk_fma_f32 v[228:229], v[206:207], v[206:207], v[228:229] op_sel_hi:[1,1,0]
	v_pk_mul_f32 v[232:233], v[204:205], v[204:205]
	v_pk_fma_f32 v[240:241], v[226:227], v[226:227], v[236:237] op_sel_hi:[1,1,0]
	v_pk_fma_f32 v[232:233], v[230:231], v[230:231], v[232:233]
	v_and_b32_e32 v239, 0xffff0000, v200
	v_mov_b32_e32 v236, v240
	v_mov_b32_e32 v242, v228
	v_mov_b32_e32 v243, v237
	v_mul_f32_e32 v213, v239, v239
	v_pk_add_f32 v[228:229], v[240:241], v[228:229]
	v_pk_mul_f32 v[240:241], v[236:237], v[242:243]
	v_pk_add_f32 v[232:233], v[232:233], v[232:233] op_sel:[0,1] op_sel_hi:[1,0]
	v_lshlrev_b32_e32 v234, 16, v202
	v_and_b32_e32 v235, 0xffff0000, v202
	v_lshlrev_b32_e32 v202, 16, v203
	v_and_b32_e32 v203, 0xffff0000, v203
	v_mov_b32_e32 v229, v241
	v_mov_b32_e32 v233, v213
	v_lshlrev_b32_e32 v200, 16, v201
	v_and_b32_e32 v201, 0xffff0000, v201
	v_pk_add_f32 v[228:229], v[228:229], v[232:233]
	v_mul_f32_e32 v232, v235, v235
	v_mul_f32_e32 v236, v203, v203
	v_mul_f32_e32 v218, v200, v200
	v_mul_f32_e32 v219, v201, v201
	v_pk_fma_f32 v[232:233], v[234:235], v[234:235], v[232:233] op_sel_hi:[1,1,0]
	v_pk_fma_f32 v[240:241], v[202:203], v[202:203], v[236:237] op_sel_hi:[1,1,0]
	v_mov_b32_e32 v233, v218
	v_mov_b32_e32 v241, v219
	v_pk_add_f32 v[232:233], v[232:233], v[240:241]
	v_lshlrev_b32_e32 v243, 16, v197
	v_pk_add_f32 v[228:229], v[228:229], v[232:233]
	v_lshlrev_b32_e32 v233, 16, v199
	v_lshlrev_b32_e32 v232, 16, v198
	v_and_b32_e32 v199, 0xffff0000, v199
	v_and_b32_e32 v198, 0xffff0000, v198
	v_pk_mul_f32 v[240:241], v[198:199], v[198:199]
	v_lshlrev_b32_e32 v242, 16, v196
	v_pk_fma_f32 v[240:241], v[232:233], v[232:233], v[240:241]
	v_and_b32_e32 v197, 0xffff0000, v197
	v_pk_add_f32 v[240:241], v[240:241], v[240:241] op_sel:[0,1] op_sel_hi:[1,0]
; #define GAS __attribute__((address_space(1)))
; DI unsigned pk2(float lo, float hi) { f32x2_t v = {lo, hi}; bf16x2_t b = __builtin_convertvector(v, bf16x2_t); return __builtin_bit_cast(unsigned, b); }
; DI void phase_norm(const Frame& F0, int nrows, const void* xlat, const void* xctx, int xin_bf16, const bf16* Y, const float* gainY, const float* gate  ,
;                    void* Xout_lat, void* Xout_ctx, int xout_bf16, bf16* Hout, const float* gainH, const float* shift, const float* scale) {
;     ...
;         if (Y) {
;             f32x4 y[8]; float ss = 0.f;
; #pragma unroll
;             for (int j = 0; j < 8; ++j) { y[j] = (f32x4){bflo(yb[j].x), bfhi(yb[j].x), bflo(yb[j].y), bfhi(yb[j].y)};
;                 ss += (y[j].x * y[j].x + y[j].y * y[j].y) + (y[j].z * y[j].z + y[j].w * y[j].w); }
;             const float rs = __builtin_amdgcn_rsqf(wave_sum(ss) * (1.0f / DM) + EPS);
; #pragma unroll
;             for (int j = 0; j < 8; ++j) v[j] = v[j] + gt[j] * (y[j] * rs);
;         }
;         if (Xout_lat) {
;             if (xout_bf16) { bf16* xo = R < NLAT ? (bf16*)Xout_lat + (size_t)R * DM : (bf16*)Xout_ctx + (size_t)(R - NLAT) * DM;
; #pragma unroll
;                 for (int j = 0; j < 8; ++j) { v2u o; o.x = pk2(v[j].x, v[j].y); o.y = pk2(v[j].z, v[j].w); *(GAS v2u*)(xo + j * 256 + co) = o; } }
;             else { float* xo = R < NLAT ? (float*)Xout_lat + (size_t)R * DM : (float*)Xout_ctx + (size_t)(R - NLAT) * DM;
; #pragma unroll
;                 for (int j = 0; j < 8; ++j) *(GAS f32x4*)(xo + j * 256 + co) = v[j]; } }
;         if (Hout) {
;             float ss = 0.f;
; #pragma unroll
;             for (int j = 0; j < 8; ++j) ss += (v[j].x * v[j].x + v[j].y * v[j].y) + (v[j].z * v[j].z + v[j].w * v[j].w);
;             const float rs = __builtin_amdgcn_rsqf(wave_sum(ss) * (1.0f / DM) + EPS);
	v_and_b32_e32 v196, 0xffff0000, v196
	v_lshlrev_b32_e32 v251, 16, v192
	v_and_b32_e32 v219, 0xffff0000, v192
	v_lshlrev_b32_e32 v220, 16, v193
	v_and_b32_e32 v221, 0xffff0000, v193
	v_pk_add_f32 v[192:193], v[228:229], v[228:229] op_sel:[0,1] op_sel_hi:[1,0]
	v_pk_mul_f32 v[244:245], v[196:197], v[196:197]
	v_lshlrev_b32_e32 v246, 16, v194
	v_and_b32_e32 v247, 0xffff0000, v194
	v_lshlrev_b32_e32 v248, 16, v195
	v_and_b32_e32 v249, 0xffff0000, v195
	v_mov_b32_e32 v250, v192
	v_mov_b32_e32 v194, v240
	v_mov_b32_e32 v195, v251
	v_pk_fma_f32 v[244:245], v[242:243], v[242:243], v[244:245]
	v_pk_add_f32 v[192:193], v[192:193], v[240:241]
	v_pk_mul_f32 v[194:195], v[250:251], v[194:195]
	v_mul_f32_e32 v213, v219, v219
	v_mov_b32_e32 v193, v195
	v_pk_add_f32 v[194:195], v[244:245], v[244:245] op_sel:[0,1] op_sel_hi:[1,0]
	v_mul_f32_e32 v218, v220, v220
	v_mov_b32_e32 v195, v213
	v_pk_add_f32 v[192:193], v[192:193], v[194:195]
	v_mul_f32_e32 v194, v247, v247
	v_pk_fma_f32 v[194:195], v[246:247], v[246:247], v[194:195] op_sel_hi:[1,1,0]
	v_mul_f32_e32 v225, v221, v221
	v_mov_b32_e32 v195, v218
	v_mul_f32_e32 v218, v249, v249
	v_pk_fma_f32 v[228:229], v[248:249], v[248:249], v[218:219] op_sel_hi:[1,1,0]
	v_mov_b32_e32 v238, v237
	v_mov_b32_e32 v229, v225
	v_pk_add_f32 v[194:195], v[194:195], v[228:229]
	v_mov_b32_e32 v218, v251
	v_pk_add_f32 v[192:193], v[192:193], v[194:195]
	s_add_i32 s4, s0, 0xffffe000
	v_add_f32_e32 v192, v192, v193
	ds_bpermute_b32 v193, v2, v192
	s_ashr_i32 s1, s0, 31
	s_cmpk_lt_i32 s0, 0x2000
	s_cselect_b32 s5, s1, 0
	s_cselect_b32 s4, s0, s4
	s_waitcnt lgkmcnt(0)
	v_add_f32_e32 v192, v192, v193
	ds_bpermute_b32 v193, v208, v192
	s_cselect_b32 s6, s19, s21
	s_cselect_b32 s7, s18, s20
	s_lshl_b64 s[4:5], s[4:5], 12
	s_add_u32 s4, s7, s4
	s_waitcnt lgkmcnt(0)
	v_add_f32_e32 v192, v192, v193
	ds_bpermute_b32 v193, v209, v192
	s_addc_u32 s5, s6, s5
	s_lshl_b64 s[0:1], s[0:1], 12
	s_addk_i32 s28, 0x400
	s_addk_i32 s29, 0x400
	s_waitcnt lgkmcnt(0)
	v_add_f32_e32 v192, v192, v193
	ds_bpermute_b32 v193, v210, v192
	s_cmp_lg_u32 s16, s25
	s_waitcnt lgkmcnt(0)
	v_add_f32_e32 v192, v192, v193
	ds_bpermute_b32 v193, v211, v192
	s_waitcnt lgkmcnt(0)
	v_add_f32_e32 v192, v192, v193
	ds_bpermute_b32 v193, v212, v192
	s_waitcnt lgkmcnt(0)
	v_add_f32_e32 v192, v192, v193
	v_fmamk_f32 v192, v192, 0x3a000000, v223
	v_rsq_f32_e32 v228, v192
	s_nop 0
	v_pk_mul_f32 v[192:193], v[228:229], v[226:227] op_sel_hi:[0,1]
	v_pk_mul_f32 v[194:195], v[228:229], v[206:207] op_sel_hi:[0,1]
	v_pk_fma_f32 v[192:193], v[16:17], v[192:193], v[120:121]
	v_mov_b32_e32 v120, v230
	v_mov_b32_e32 v121, v204
	v_mov_b32_e32 v204, v231
	v_pk_fma_f32 v[122:123], v[18:19], v[194:195], v[122:123]
	v_pk_mul_f32 v[120:121], v[228:229], v[120:121] op_sel_hi:[0,1]
	v_pk_mul_f32 v[194:195], v[228:229], v[204:205] op_sel_hi:[0,1]
	v_pk_fma_f32 v[118:119], v[14:15], v[194:195], v[118:119]
	v_pk_fma_f32 v[194:195], v[12:13], v[120:121], v[116:117]
	v_pk_mul_f32 v[116:117], v[228:229], v[202:203] op_sel_hi:[0,1]
	v_pk_mul_f32 v[120:121], v[228:229], v[234:235] op_sel_hi:[0,1]
	v_pk_fma_f32 v[116:117], v[10:11], v[116:117], v[130:131]
	v_pk_mul_f32 v[130:131], v[238:239], v[228:229] op_sel_hi:[1,0]
	v_pk_fma_f32 v[128:129], v[8:9], v[120:121], v[128:129]
	v_pk_mul_f32 v[120:121], v[200:201], v[228:229] op_sel_hi:[1,0]
	v_pk_fma_f32 v[130:131], v[4:5], v[130:131], v[124:125]
	v_mov_b32_e32 v124, v232
	v_mov_b32_e32 v125, v198
	v_pk_fma_f32 v[120:121], v[6:7], v[120:121], v[126:127]
	v_pk_mul_f32 v[126:127], v[228:229], v[124:125] op_sel_hi:[0,1]
	v_mov_b32_e32 v198, v233
	v_pk_fma_f32 v[136:137], v[32:33], v[126:127], v[136:137]
	v_mov_b32_e32 v126, v242
	v_mov_b32_e32 v127, v196
	v_pk_mul_f32 v[124:125], v[228:229], v[198:199] op_sel_hi:[0,1]
	v_pk_mul_f32 v[126:127], v[228:229], v[126:127] op_sel_hi:[0,1]
	v_mov_b32_e32 v196, v243
	v_pk_fma_f32 v[124:125], v[34:35], v[124:125], v[138:139]
	v_pk_mul_f32 v[138:139], v[228:229], v[196:197] op_sel_hi:[0,1]
	v_pk_fma_f32 v[196:197], v[28:29], v[126:127], v[132:133]
	v_pk_mul_f32 v[132:133], v[228:229], v[246:247] op_sel_hi:[0,1]
	v_pk_fma_f32 v[134:135], v[30:31], v[138:139], v[134:135]
	v_pk_fma_f32 v[138:139], v[24:25], v[132:133], v[148:149]
	v_pk_mul_f32 v[148:149], v[218:219], v[228:229] op_sel_hi:[1,0]
	v_pk_mul_f32 v[126:127], v[228:229], v[248:249] op_sel_hi:[0,1]
	v_pk_mul_f32 v[132:133], v[220:221], v[228:229] op_sel_hi:[1,0]
	v_pk_fma_f32 v[140:141], v[20:21], v[148:149], v[140:141]
	v_mov_b32_e32 v148, v193
	v_mov_b32_e32 v149, v195
	v_pk_fma_f32 v[126:127], v[26:27], v[126:127], v[150:151]
	v_pk_fma_f32 v[132:133], v[22:23], v[132:133], v[142:143]
	v_mov_b32_e32 v142, v192
	v_mov_b32_e32 v143, v194
	v_pk_mul_f32 v[148:149], v[148:149], v[148:149]
	v_mov_b32_e32 v150, v123
	v_mov_b32_e32 v151, v119
	v_pk_fma_f32 v[142:143], v[142:143], v[142:143], v[148:149]
	v_mov_b32_e32 v148, v122
	v_mov_b32_e32 v149, v118
	v_pk_mul_f32 v[150:151], v[150:151], v[150:151]
	v_pk_fma_f32 v[148:149], v[148:149], v[148:149], v[150:151]
	v_pk_mul_f32 v[150:151], v[128:129], v[128:129]
	v_pk_add_f32 v[142:143], v[142:143], v[148:149]
	v_pk_mul_f32 v[148:149], v[116:117], v[116:117]
	v_pk_add_f32 v[142:143], v[142:143], v[142:143] op_sel_hi:[0,1]
	v_pk_mov_b32 v[198:199], v[150:151], v[148:149] op_sel:[1,0]
	v_mov_b32_e32 v151, v149
	v_mul_f32_e32 v142, v130, v130
	v_pk_add_f32 v[148:149], v[198:199], v[150:151]
	v_pk_fma_f32 v[150:151], v[130:131], v[130:131], v[142:143] op_sel_hi:[1,1,0]
	v_mul_f32_e32 v142, v120, v120
	v_pk_add_f32 v[148:149], v[148:149], v[148:149] op_sel_hi:[0,1]
	v_pk_fma_f32 v[198:199], v[120:121], v[120:121], v[142:143] op_sel_hi:[1,1,0]
	v_mul_f32_e32 v150, v136, v136
	v_mul_f32_e32 v198, v137, v137
	v_mul_f32_e32 v148, v124, v124
	v_mul_f32_e32 v142, v125, v125
	v_pk_add_f32 v[150:151], v[150:151], v[198:199]
	v_pk_add_f32 v[142:143], v[148:149], v[142:143]
	v_pk_mul_f32 v[148:149], v[134:135], v[134:135]
	v_pk_add_f32 v[142:143], v[150:151], v[142:143]
	v_pk_mul_f32 v[150:151], v[196:197], v[196:197]
	v_pk_add_f32 v[142:143], v[142:143], v[142:143] op_sel_hi:[0,1]
	v_pk_mov_b32 v[198:199], v[150:151], v[148:149] op_sel:[1,0]
	v_mov_b32_e32 v151, v149
	v_mul_f32_e32 v142, v138, v138
	v_pk_add_f32 v[148:149], v[198:199], v[150:151]
	v_pk_fma_f32 v[150:151], v[138:139], v[138:139], v[142:143] op_sel_hi:[1,1,0]
	v_mul_f32_e32 v142, v126, v126
	v_pk_add_f32 v[148:149], v[148:149], v[148:149] op_sel_hi:[0,1]
	v_pk_fma_f32 v[198:199], v[126:127], v[126:127], v[142:143] op_sel_hi:[1,1,0]
	v_mul_f32_e32 v150, v140, v140
	v_mul_f32_e32 v198, v141, v141
	v_mul_f32_e32 v148, v132, v132
	v_mul_f32_e32 v142, v133, v133
	v_pk_add_f32 v[150:151], v[150:151], v[198:199]
	v_pk_add_f32 v[142:143], v[148:149], v[142:143]
	v_cvt_pk_bf16_f32 v148, v192, v193
	v_pk_add_f32 v[142:143], v[150:151], v[142:143]
	v_add_f32_e32 v149, v142, v143
	ds_bpermute_b32 v150, v2, v149
	v_lshl_add_u64 v[142:143], v[164:165], 1, s[4:5]
	s_waitcnt lgkmcnt(0)
; #define GAS __attribute__((address_space(1)))
; DI unsigned pk2(float lo, float hi) { f32x2_t v = {lo, hi}; bf16x2_t b = __builtin_convertvector(v, bf16x2_t); return __builtin_bit_cast(unsigned, b); }
; DI void phase_norm(const Frame& F0, int nrows, const void* xlat, const void* xctx, int xin_bf16, const bf16* Y, const float* gainY, const float* gate  ,
;                    void* Xout_lat, void* Xout_ctx, int xout_bf16, bf16* Hout, const float* gainH, const float* shift, const float* scale) {
;     ...
;         if (Xout_lat) {
;             if (xout_bf16) { bf16* xo = R < NLAT ? (bf16*)Xout_lat + (size_t)R * DM : (bf16*)Xout_ctx + (size_t)(R - NLAT) * DM;
; #pragma unroll
;                 for (int j = 0; j < 8; ++j) { v2u o; o.x = pk2(v[j].x, v[j].y); o.y = pk2(v[j].z, v[j].w); *(GAS v2u*)(xo + j * 256 + co) = o; } }
;             else { float* xo = R < NLAT ? (float*)Xout_lat + (size_t)R * DM : (float*)Xout_ctx + (size_t)(R - NLAT) * DM;
; #pragma unroll
;                 for (int j = 0; j < 8; ++j) *(GAS f32x4*)(xo + j * 256 + co) = v[j]; } }
;         if (Hout) {
;             float ss = 0.f;
; #pragma unroll
;             for (int j = 0; j < 8; ++j) ss += (v[j].x * v[j].x + v[j].y * v[j].y) + (v[j].z * v[j].z + v[j].w * v[j].w);
;             const float rs = __builtin_amdgcn_rsqf(wave_sum(ss) * (1.0f / DM) + EPS);
;             v2u o[8];
; #pragma unroll
;             for (int j = 0; j < 8; ++j) { const f32x4 h = (v[j] * rs) * sc[j] + sh[j]; o[j].x = pk2(h.x, h.y); o[j].y = pk2(h.z, h.w); }
; #pragma unroll
;             for (int j = 0; j < 8; ++j) *(GAS v2u*)(Hout + (size_t)R * DM + j * 256 + co) = o[j];
;         }
; #pragma unroll
;         for (int j = 0; j < 8; ++j) { v[j] = vn[j]; yb[j] = ybn[j]; }
	v_add_f32_e32 v150, v149, v150
	ds_bpermute_b32 v151, v208, v150
	v_cvt_pk_bf16_f32 v149, v122, v123
	global_store_dwordx2 v[142:143], v[148:149], off
	v_cvt_pk_bf16_f32 v148, v194, v195
	v_cvt_pk_bf16_f32 v149, v118, v119
	s_waitcnt lgkmcnt(0)
	v_add_f32_e32 v150, v150, v151
	ds_bpermute_b32 v151, v209, v150
	global_store_dwordx2 v[142:143], v[148:149], off offset:512
	v_cvt_pk_bf16_f32 v148, v128, v129
	v_cvt_pk_bf16_f32 v149, v116, v117
	global_store_dwordx2 v[142:143], v[148:149], off offset:1024
	s_waitcnt lgkmcnt(0)
	v_add_f32_e32 v150, v150, v151
	ds_bpermute_b32 v151, v210, v150
	v_cvt_pk_bf16_f32 v148, v130, v131
	v_cvt_pk_bf16_f32 v149, v120, v121
	global_store_dwordx2 v[142:143], v[148:149], off offset:1536
	v_cvt_pk_bf16_f32 v148, v136, v137
	s_waitcnt lgkmcnt(0)
	v_add_f32_e32 v150, v150, v151
	ds_bpermute_b32 v151, v211, v150
	v_cvt_pk_bf16_f32 v149, v124, v125
	global_store_dwordx2 v[142:143], v[148:149], off offset:2048
	v_cvt_pk_bf16_f32 v148, v196, v197
	v_cvt_pk_bf16_f32 v149, v134, v135
	s_waitcnt lgkmcnt(0)
	v_add_f32_e32 v150, v150, v151
	ds_bpermute_b32 v151, v212, v150
	global_store_dwordx2 v[142:143], v[148:149], off offset:2560
	v_cvt_pk_bf16_f32 v148, v138, v139
	v_cvt_pk_bf16_f32 v149, v126, v127
	global_store_dwordx2 v[142:143], v[148:149], off offset:3072
	s_waitcnt lgkmcnt(0)
	v_add_f32_e32 v148, v150, v151
	v_fmamk_f32 v148, v148, 0x3a000000, v223
	v_rsq_f32_e32 v148, v148
	v_cvt_pk_bf16_f32 v150, v140, v141
	v_cvt_pk_bf16_f32 v151, v132, v133
	global_store_dwordx2 v[142:143], v[150:151], off offset:3584
	v_pk_mul_f32 v[142:143], v[192:193], v[148:149] op_sel_hi:[1,0]
	v_pk_mul_f32 v[122:123], v[122:123], v[148:149] op_sel_hi:[1,0]
	v_pk_fma_f32 v[142:143], v[56:57], v[142:143], v[36:37]
	v_pk_fma_f32 v[122:123], v[58:59], v[122:123], v[38:39]
	v_cvt_pk_bf16_f32 v142, v142, v143
	v_cvt_pk_bf16_f32 v143, v122, v123
	v_pk_mul_f32 v[122:123], v[194:195], v[148:149] op_sel_hi:[1,0]
	v_pk_mul_f32 v[118:119], v[118:119], v[148:149] op_sel_hi:[1,0]
	v_pk_fma_f32 v[122:123], v[52:53], v[122:123], v[40:41]
	v_pk_fma_f32 v[118:119], v[54:55], v[118:119], v[42:43]
	v_cvt_pk_bf16_f32 v122, v122, v123
	v_cvt_pk_bf16_f32 v123, v118, v119
	v_pk_mul_f32 v[118:119], v[128:129], v[148:149] op_sel_hi:[1,0]
	v_pk_mul_f32 v[116:117], v[116:117], v[148:149] op_sel_hi:[1,0]
	v_pk_fma_f32 v[118:119], v[64:65], v[118:119], v[44:45]
	v_pk_fma_f32 v[116:117], v[66:67], v[116:117], v[46:47]
	v_cvt_pk_bf16_f32 v118, v118, v119
	v_cvt_pk_bf16_f32 v119, v116, v117
	v_pk_mul_f32 v[116:117], v[130:131], v[148:149] op_sel_hi:[1,0]
	v_pk_mul_f32 v[120:121], v[120:121], v[148:149] op_sel_hi:[1,0]
	v_pk_fma_f32 v[116:117], v[60:61], v[116:117], v[48:49]
	v_pk_fma_f32 v[120:121], v[62:63], v[120:121], v[50:51]
	v_cvt_pk_bf16_f32 v116, v116, v117
	v_cvt_pk_bf16_f32 v117, v120, v121
	v_pk_mul_f32 v[120:121], v[136:137], v[148:149] op_sel_hi:[1,0]
	v_pk_mul_f32 v[124:125], v[124:125], v[148:149] op_sel_hi:[1,0]
	v_pk_fma_f32 v[120:121], v[92:93], v[120:121], v[68:69]
	v_pk_fma_f32 v[124:125], v[94:95], v[124:125], v[70:71]
	v_cvt_pk_bf16_f32 v120, v120, v121
	v_cvt_pk_bf16_f32 v121, v124, v125
	v_pk_mul_f32 v[124:125], v[196:197], v[148:149] op_sel_hi:[1,0]
	v_pk_mul_f32 v[128:129], v[134:135], v[148:149] op_sel_hi:[1,0]
	v_pk_fma_f32 v[124:125], v[88:89], v[124:125], v[72:73]
	v_pk_fma_f32 v[128:129], v[90:91], v[128:129], v[74:75]
	v_cvt_pk_bf16_f32 v124, v124, v125
	v_cvt_pk_bf16_f32 v125, v128, v129
	v_pk_mul_f32 v[128:129], v[138:139], v[148:149] op_sel_hi:[1,0]
	v_pk_mul_f32 v[126:127], v[126:127], v[148:149] op_sel_hi:[1,0]
	v_pk_fma_f32 v[128:129], v[100:101], v[128:129], v[76:77]
	v_pk_fma_f32 v[126:127], v[102:103], v[126:127], v[78:79]
	v_cvt_pk_bf16_f32 v128, v128, v129
	v_cvt_pk_bf16_f32 v129, v126, v127
	v_pk_mul_f32 v[126:127], v[140:141], v[148:149] op_sel_hi:[1,0]
	v_pk_mul_f32 v[130:131], v[132:133], v[148:149] op_sel_hi:[1,0]
	v_pk_fma_f32 v[126:127], v[96:97], v[126:127], v[80:81]
	v_pk_fma_f32 v[130:131], v[98:99], v[130:131], v[82:83]
	v_cvt_pk_bf16_f32 v126, v126, v127
	v_cvt_pk_bf16_f32 v127, v130, v131
	v_lshl_add_u64 v[130:131], v[174:175], 0, s[0:1]
	global_store_dwordx2 v[130:131], v[142:143], off
	global_store_dwordx2 v[130:131], v[122:123], off offset:512
	global_store_dwordx2 v[130:131], v[118:119], off offset:1024
	global_store_dwordx2 v[130:131], v[116:117], off offset:1536
	global_store_dwordx2 v[130:131], v[120:121], off offset:2048
	global_store_dwordx2 v[130:131], v[124:125], off offset:2560
	global_store_dwordx2 v[130:131], v[128:129], off offset:3072
	global_store_dwordx2 v[130:131], v[126:127], off offset:3584
	s_waitcnt vmcnt(16)
	s_mov_b64 vcc, s[88:89]
	s_cbranch_vccnz .Lnorm_nounp_B
	v_lshlrev_b32_e32 v84, 16, v86
	v_and_b32_e32 v85, 0xffff0000, v86
	v_lshlrev_b32_e32 v86, 16, v87
	v_and_b32_e32 v87, 0xffff0000, v87
	v_lshlrev_b32_e32 v104, 16, v106
	v_and_b32_e32 v105, 0xffff0000, v106
	v_lshlrev_b32_e32 v106, 16, v107
	v_and_b32_e32 v107, 0xffff0000, v107
	v_lshlrev_b32_e32 v108, 16, v110
	v_and_b32_e32 v109, 0xffff0000, v110
	v_lshlrev_b32_e32 v110, 16, v111
	v_and_b32_e32 v111, 0xffff0000, v111
	v_lshlrev_b32_e32 v112, 16, v114
	v_and_b32_e32 v113, 0xffff0000, v114
	v_lshlrev_b32_e32 v114, 16, v115
	v_and_b32_e32 v115, 0xffff0000, v115
	v_lshlrev_b32_e32 v144, 16, v146
	v_and_b32_e32 v145, 0xffff0000, v146
	v_lshlrev_b32_e32 v146, 16, v147
	v_and_b32_e32 v147, 0xffff0000, v147
	v_lshlrev_b32_e32 v152, 16, v154
	v_and_b32_e32 v153, 0xffff0000, v154
	v_lshlrev_b32_e32 v154, 16, v155
	v_and_b32_e32 v155, 0xffff0000, v155
	v_lshlrev_b32_e32 v156, 16, v158
	v_and_b32_e32 v157, 0xffff0000, v158
	v_lshlrev_b32_e32 v158, 16, v159
	v_and_b32_e32 v159, 0xffff0000, v159
	v_lshlrev_b32_e32 v160, 16, v162
	v_and_b32_e32 v161, 0xffff0000, v162
	v_lshlrev_b32_e32 v162, 16, v163
	v_and_b32_e32 v163, 0xffff0000, v163
.Lnorm_nounp_B:
	v_mov_b64_e32 v[206:207], v[176:177]
	v_mov_b64_e32 v[204:205], v[178:179]
	v_mov_b64_e32 v[202:203], v[180:181]
	v_mov_b64_e32 v[200:201], v[182:183]
	v_mov_b64_e32 v[198:199], v[184:185]
	v_mov_b64_e32 v[196:197], v[186:187]
	v_mov_b64_e32 v[194:195], v[188:189]
	v_mov_b64_e32 v[192:193], v[190:191]
	v_mov_b32_e32 v120, v84
	v_mov_b32_e32 v121, v85
	v_mov_b32_e32 v122, v86
	v_mov_b32_e32 v123, v87
	v_mov_b32_e32 v116, v104
	v_mov_b32_e32 v117, v105
	v_mov_b32_e32 v118, v106
	v_mov_b32_e32 v119, v107
	v_mov_b32_e32 v128, v108
	v_mov_b32_e32 v129, v109
	v_mov_b32_e32 v130, v110
	v_mov_b32_e32 v131, v111
	v_mov_b32_e32 v124, v112
	v_mov_b32_e32 v125, v113
	v_mov_b32_e32 v126, v114
	v_mov_b32_e32 v127, v115
	v_mov_b32_e32 v136, v144
	v_mov_b32_e32 v137, v145
	v_mov_b32_e32 v138, v146
	v_mov_b32_e32 v139, v147
	v_mov_b32_e32 v132, v152
	v_mov_b32_e32 v133, v153
	v_mov_b32_e32 v134, v154
	v_mov_b32_e32 v135, v155
	v_mov_b32_e32 v148, v156
	v_mov_b32_e32 v149, v157
	v_mov_b32_e32 v150, v158
	v_mov_b32_e32 v151, v159
	v_mov_b32_e32 v140, v160
	v_mov_b32_e32 v141, v161
	v_mov_b32_e32 v142, v162
	v_mov_b32_e32 v143, v163
	s_cbranch_scc0 .LBB0_1065

; #define GAS __attribute__((address_space(1)))
; DI void norm_load_x(f32x4 (&v)[8], const void* xlat, const void* xctx, int xin_bf16, int R, int co) {
;     if (xin_bf16) { const bf16* xr = R < NLAT ? (const bf16*)xlat + (size_t)R * DM : (const bf16*)xctx + (size_t)(R - NLAT) * DM;
;         v2u t[8];
; #pragma unroll
;         for (int j = 0; j < 8; ++j) t[j] = *(const GAS v2u*)(xr + j * 256 + co);
; #pragma unroll
;         for (int j = 0; j < 8; ++j) v[j] = (f32x4){bflo(t[j].x), bfhi(t[j].x), bflo(t[j].y), bfhi(t[j].y)}; }
; DI void phase_norm(const Frame& F0, int nrows, const void* xlat, const void* xctx, int xin_bf16, const bf16* Y, const float* gainY, const float* gate  ,
;                    void* Xout_lat, void* Xout_ctx, int xout_bf16, bf16* Hout, const float* gainH, const float* shift, const float* scale) {
;     ...
;         const int R = NORM_ROW(it); const int mb = row_mb(R), Rn = NORM_ROW(it + 1);
;         f32x4 vn[8]; v2u ybn[8];
;         if (it + 1 < nit) { norm_load_x(vn, xlat, xctx, xin_bf16, Rn, co);
;             if (Y) {
; #pragma unroll
;                 for (int j = 0; j < 8; ++j) ybn[j] = *(const GAS v2u*)(Y + (size_t)Rn * DM + j * 256 + co); } }
.LBB0_1084:
	s_cmp_ge_i32 s25, s16
	s_cbranch_scc1 .LBB0_1089
	s_add_i32 s1, s4, 0xffffe000
	s_ashr_i32 s5, s4, 31
	s_cmpk_lt_i32 s4, 0x2000
	s_cselect_b32 s7, s5, 0
	s_cselect_b32 s6, s4, s1
	s_cselect_b32 s1, s37, s59
	s_cselect_b32 s22, s36, s58
	s_and_b64 vcc, exec, s[88:89]
	s_cbranch_vccnz .LBB0_1091
	s_lshl_b64 s[8:9], s[6:7], 12
	s_add_u32 s8, s22, s8
	s_addc_u32 s9, s1, s9
	v_lshl_add_u64 v[84:85], v[164:165], 1, s[8:9]
	global_load_dwordx2 v[86:87], v[84:85], off nt
	global_load_dwordx2 v[106:107], v[84:85], off offset:512 nt
	global_load_dwordx2 v[110:111], v[84:85], off offset:1024 nt
	global_load_dwordx2 v[114:115], v[84:85], off offset:1536 nt
	global_load_dwordx2 v[146:147], v[84:85], off offset:2048 nt
	global_load_dwordx2 v[154:155], v[84:85], off offset:2560 nt
	global_load_dwordx2 v[158:159], v[84:85], off offset:3072 nt
	global_load_dwordx2 v[162:163], v[84:85], off offset:3584 nt
	s_cbranch_execnz .LBB0_1088

; #define GAS __attribute__((address_space(1)))
; DI void phase_norm(const Frame& F0, int nrows, const void* xlat, const void* xctx, int xin_bf16, const bf16* Y, const float* gainY, const float* gate  ,
;                    void* Xout_lat, void* Xout_ctx, int xout_bf16, bf16* Hout, const float* gainH, const float* shift, const float* scale) {
;     ...
;         if (mb != mbp) { mbp = mb;
;             if (Y) {
; #pragma unroll
;                 for (int j = 0; j < 8; ++j) gt[j] = *(const GAS f32x4*)(gate + (size_t)mb * NADA + j * 256 + co); }
;             if (Hout) {
; #pragma unroll
;                 for (int j = 0; j < 8; ++j) { sh[j] = *(const GAS f32x4*)(shift + (size_t)mb * NADA + j * 256 + co); sc[j] = *(const GAS f32x4*)(scale + (size_t)mb * NADA + j * 256 + co); } } }
.LBB0_1089:
	s_cmpk_lt_u32 s0, 0x2000
	s_cselect_b32 s1, 1, 2
	s_cmpk_gt_i32 s0, 0xfff
	s_cselect_b32 s1, s1, 0
	s_cmp_eq_u32 s1, s10
	s_cbranch_scc1 .LBB0_1077
	s_mul_i32 s10, s1, 0xc000
	v_lshl_add_u64 v[20:21], v[168:169], 0, s[10:11]
	global_load_dwordx4 v[16:19], v[20:21], off
	global_load_dwordx4 v[12:15], v[20:21], off offset:1024
	global_load_dwordx4 v[8:11], v[20:21], off offset:2048
	global_load_dwordx4 v[4:7], v[20:21], off offset:3072
	v_add_co_u32_e32 v20, vcc, 0x1000, v20
	v_lshl_add_u64 v[68:69], v[170:171], 0, s[10:11]
	s_nop 0
	v_addc_co_u32_e32 v21, vcc, 0, v21, vcc
	s_movk_i32 s4, 0x1000
	v_add_co_u32_e32 v80, vcc, s4, v68
	v_lshl_add_u64 v[70:71], v[172:173], 0, s[10:11]
	s_nop 0
	v_addc_co_u32_e32 v81, vcc, 0, v69, vcc
	v_add_co_u32_e32 v96, vcc, 0x1000, v70
	global_load_dwordx4 v[32:35], v[20:21], off
	global_load_dwordx4 v[28:31], v[20:21], off offset:1024
	global_load_dwordx4 v[24:27], v[20:21], off offset:2048
	s_nop 0
	global_load_dwordx4 v[20:23], v[20:21], off offset:3072
	v_addc_co_u32_e32 v97, vcc, 0, v71, vcc
	global_load_dwordx4 v[36:39], v[68:69], off
	global_load_dwordx4 v[40:43], v[68:69], off offset:1024
	global_load_dwordx4 v[56:59], v[70:71], off
	global_load_dwordx4 v[52:55], v[70:71], off offset:1024
	global_load_dwordx4 v[44:47], v[68:69], off offset:2048
	global_load_dwordx4 v[48:51], v[68:69], off offset:3072
	global_load_dwordx4 v[64:67], v[70:71], off offset:2048
	global_load_dwordx4 v[60:63], v[70:71], off offset:3072
	s_nop 0
	global_load_dwordx4 v[68:71], v[80:81], off
	global_load_dwordx4 v[72:75], v[80:81], off offset:1024
	global_load_dwordx4 v[92:95], v[96:97], off
	global_load_dwordx4 v[88:91], v[96:97], off offset:1024
	global_load_dwordx4 v[76:79], v[80:81], off offset:2048
	s_nop 0
	global_load_dwordx4 v[80:83], v[80:81], off offset:3072
	s_nop 0
	global_load_dwordx4 v[100:103], v[96:97], off offset:2048
	s_nop 0
	global_load_dwordx4 v[96:99], v[96:97], off offset:3072
	s_mov_b32 s10, s1
	s_waitcnt vmcnt(0)
	s_branch .LBB0_1077
